# baseline (speedup 1.0000x reference)
.LBB0_756:
	s_or_b64 exec, exec, s[6:7]
	s_waitcnt vmcnt(0)
	buffer_inv sc0

.LBB0_774:
	s_or_b64 exec, exec, s[4:5]
	s_mov_b64 s[4:5], exec
	v_mbcnt_lo_u32_b32 v1, s4, 0
	v_mbcnt_hi_u32_b32 v1, s5, v1
	s_mov_b32 s9, 0
	v_cmp_eq_u32_e32 vcc, 0, v1
	s_waitcnt vmcnt(0)
	buffer_inv sc0
	s_and_saveexec_b64 s[6:7], vcc
	s_cbranch_execz .LBB0_776
	s_add_i32 s8, s3, 0x900
	s_lshl_b64 s[8:9], s[8:9], 2
	s_add_u32 s8, s88, s8
	s_addc_u32 s9, s89, s9
	s_bcnt1_i32_b64 s3, s[4:5]
	v_mov_b32_e32 v1, 0
	v_mov_b32_e32 v2, s3
	global_atomic_add v1, v2, s[8:9]
